# latent attention PV: transposed V fragment reads issued three fragments ahead of their MFMAs
# baseline (speedup 1.0000x reference)
.LBB0_140:
	ds_read_b64_tr_b16 v[68:69], v242 offset:9216
	ds_read_b64_tr_b16 v[70:71], v242 offset:10368
	ds_read_b64_tr_b16 v[72:73], v242 offset:9280
	ds_read_b64_tr_b16 v[74:75], v242 offset:10432
	ds_read_b64_tr_b16 v[76:77], v242 offset:11520
	ds_read_b64_tr_b16 v[78:79], v242 offset:12672
	v_sub_f32_e32 v48, v172, v1
	v_exp_f32_e32 v51, v48
	v_sub_f32_e32 v49, v173, v1
	v_exp_f32_e32 v52, v49
	v_sub_f32_e32 v14, v14, v1
	v_exp_f32_e32 v53, v14
	v_sub_f32_e32 v15, v15, v1
	v_exp_f32_e32 v56, v15
	v_sub_f32_e32 v10, v10, v1
	v_add_f32_e32 v48, 0, v51
	v_exp_f32_e32 v54, v10
	v_sub_f32_e32 v11, v11, v1
	v_add_f32_e32 v48, v52, v48
	v_exp_f32_e32 v57, v11
	v_sub_f32_e32 v11, v12, v1
	v_add_f32_e32 v14, v53, v48
	v_exp_f32_e32 v55, v11
	v_sub_f32_e32 v11, v13, v1
	v_add_f32_e32 v14, v56, v14
	v_exp_f32_e32 v58, v11
	v_add_f32_e32 v10, v54, v14
	v_add_f32_e32 v10, v57, v10
	v_add_f32_e32 v10, v55, v10
	v_add_f32_e32 v10, v58, v10
	v_cvt_pk_bf16_f32 v55, v55, v58
	v_cvt_pk_bf16_f32 v54, v54, v57
	v_cvt_pk_bf16_f32 v53, v53, v56
	s_nop 0
	s_nop 0
	v_sub_f32_e32 v3, v3, v1
	v_exp_f32_e32 v61, v3
	v_sub_f32_e32 v3, v4, v1
	v_cvt_pk_bf16_f32 v52, v51, v52
	v_exp_f32_e32 v62, v3
	v_sub_f32_e32 v3, v5, v1
	s_nop 0
	s_waitcnt lgkmcnt(4)
	v_mfma_f32_32x32x16_bf16 v[32:47], v[68:71], v[52:55], v[32:47]
	ds_read_b64_tr_b16 v[68:69], v242 offset:11584
	ds_read_b64_tr_b16 v[70:71], v242 offset:12736
	s_nop 0
	s_nop 0
	v_exp_f32_e32 v63, v3
	v_sub_f32_e32 v3, v6, v1
	v_exp_f32_e32 v64, v3
	v_sub_f32_e32 v3, v7, v1
	v_exp_f32_e32 v65, v3
	v_sub_f32_e32 v3, v8, v1
	v_sub_f32_e32 v2, v2, v1
	v_exp_f32_e32 v66, v3
	v_sub_f32_e32 v3, v9, v1
	v_exp_f32_e32 v60, v2
	v_exp_f32_e32 v67, v3
	s_nop 0
	s_waitcnt lgkmcnt(4)
	v_mfma_f32_32x32x16_bf16 v[16:31], v[72:75], v[52:55], v[16:31]
	ds_read_b64_tr_b16 v[72:73], v242 offset:13824
	ds_read_b64_tr_b16 v[74:75], v242 offset:14976
	s_nop 0
	s_nop 0
	v_cvt_pk_bf16_f32 v54, v64, v65
	v_cvt_pk_bf16_f32 v55, v66, v67
	v_cvt_pk_bf16_f32 v53, v62, v63
	v_cvt_pk_bf16_f32 v52, v60, v61
	v_add_f32_e32 v2, v60, v10
	v_sub_f32_e32 v3, v174, v1
	s_nop 0
	s_waitcnt lgkmcnt(4)
	v_mfma_f32_32x32x16_bf16 v[32:47], v[76:79], v[52:55], v[32:47]
	ds_read_b64_tr_b16 v[76:77], v242 offset:13888
	ds_read_b64_tr_b16 v[78:79], v242 offset:15040
	s_nop 0
	s_nop 0
	v_sub_f32_e32 v4, v175, v1
	v_sub_f32_e32 v5, v176, v1
	v_sub_f32_e32 v6, v177, v1
	v_sub_f32_e32 v7, v178, v1
	v_sub_f32_e32 v8, v179, v1
	v_sub_f32_e32 v9, v180, v1
	v_sub_f32_e32 v10, v181, v1
	v_exp_f32_e32 v3, v3
	v_exp_f32_e32 v4, v4
	v_exp_f32_e32 v5, v5
	v_exp_f32_e32 v6, v6
	v_exp_f32_e32 v7, v7
	v_exp_f32_e32 v8, v8
	v_exp_f32_e32 v9, v9
	v_exp_f32_e32 v10, v10
	s_nop 0
	s_waitcnt lgkmcnt(4)
	v_mfma_f32_32x32x16_bf16 v[16:31], v[68:71], v[52:55], v[16:31]
	ds_read_b64_tr_b16 v[68:69], v242 offset:16128
	ds_read_b64_tr_b16 v[70:71], v242 offset:17280
	s_nop 0
	s_nop 0
	v_add_f32_e32 v2, v61, v2
	v_cvt_pk_bf16_f32 v55, v9, v10
	v_cvt_pk_bf16_f32 v54, v7, v8
	v_cvt_pk_bf16_f32 v53, v5, v6
	v_cvt_pk_bf16_f32 v52, v3, v4
	v_add_f32_e32 v2, v62, v2
	v_add_f32_e32 v2, v63, v2
	s_nop 0
	s_waitcnt lgkmcnt(4)
	v_mfma_f32_32x32x16_bf16 v[32:47], v[72:75], v[52:55], v[32:47]
	ds_read_b64_tr_b16 v[72:73], v242 offset:16192
	ds_read_b64_tr_b16 v[74:75], v242 offset:17344
	s_nop 0
	s_nop 0
	v_add_f32_e32 v2, v64, v2
	v_add_f32_e32 v2, v65, v2
	v_add_f32_e32 v2, v66, v2
	v_sub_f32_e32 v11, v182, v1
	v_sub_f32_e32 v12, v183, v1
	v_sub_f32_e32 v13, v184, v1
	v_sub_f32_e32 v14, v185, v1
	v_sub_f32_e32 v15, v186, v1
	v_sub_f32_e32 v48, v187, v1
	v_sub_f32_e32 v49, v188, v1
	v_sub_f32_e32 v50, v189, v1
	v_add_f32_e32 v2, v67, v2
	v_exp_f32_e32 v11, v11
	v_exp_f32_e32 v12, v12
	v_exp_f32_e32 v13, v13
	v_exp_f32_e32 v14, v14
	v_exp_f32_e32 v15, v15
	v_exp_f32_e32 v48, v48
	v_exp_f32_e32 v49, v49
	v_exp_f32_e32 v50, v50
	s_nop 0
	s_waitcnt lgkmcnt(4)
	v_mfma_f32_32x32x16_bf16 v[16:31], v[76:79], v[52:55], v[16:31]
	s_nop 0
	s_nop 0
	v_add_f32_e32 v2, v3, v2
	v_add_f32_e32 v2, v4, v2
	v_add_f32_e32 v2, v5, v2
	v_cvt_pk_bf16_f32 v55, v49, v50
	v_cvt_pk_bf16_f32 v54, v15, v48
	v_cvt_pk_bf16_f32 v53, v13, v14
	v_cvt_pk_bf16_f32 v52, v11, v12
	v_add_f32_e32 v2, v6, v2
	v_add_f32_e32 v2, v7, v2
	s_nop 0
	s_waitcnt lgkmcnt(2)
	v_mfma_f32_32x32x16_bf16 v[32:47], v[68:71], v[52:55], v[32:47]
	s_nop 0
	s_nop 0
	v_add_f32_e32 v2, v8, v2
	v_add_f32_e32 v2, v9, v2
	v_add_f32_e32 v2, v10, v2
	v_add_f32_e32 v2, v11, v2
	v_add_f32_e32 v2, v12, v2
	v_add_f32_e32 v2, v13, v2
	s_nop 0
	s_waitcnt lgkmcnt(0)
	v_mfma_f32_32x32x16_bf16 v[16:31], v[72:75], v[52:55], v[16:31]
	v_add_f32_e32 v2, v14, v2
	v_add_f32_e32 v2, v15, v2
	v_add_f32_e32 v2, v48, v2
	v_add_f32_e32 v2, v49, v2
	v_add_f32_e32 v2, v50, v2
	v_add_f32_e32 v243, v2, v243
	v_mov_b32_e32 v244, v1
